# XCC-local barriers poll the arrival counter directly (one L2 round trip less per seam), on top of v42
# speedup vs baseline: 1.0062x; 1.0041x over previous
.LBB0_351:
	s_or_b64 exec, exec, s[6:7]
	s_waitcnt lgkmcnt(0)
	v_cvt_f32_u32_e32 v4, v2
	s_waitcnt vmcnt(0)
	v_readfirstlane_b32 s4, v3
	s_mov_b64 s[6:7], 0
	v_rcp_iflag_f32_e32 v4, v4
	v_add_u32_e32 v1, s4, v1
	v_add_u32_e32 v5, 1, v1
	s_add_u32 s4, s2, 0x3600
	v_mul_f32_e32 v3, 0x4f7ffffe, v4
	v_cvt_u32_f32_e32 v3, v3
	v_sub_u32_e32 v4, 0, v2
	s_addc_u32 s5, s3, 0
	v_mul_lo_u32 v4, v4, v3
	v_mul_hi_u32 v4, v3, v4
	v_add_u32_e32 v3, v3, v4
	v_mul_hi_u32 v3, v1, v3
	v_mul_lo_u32 v4, v3, v2
	v_sub_u32_e32 v1, v1, v4
	v_add_u32_e32 v6, 1, v3
	v_cmp_ge_u32_e32 vcc, v1, v2
	v_sub_u32_e32 v4, v1, v2
	s_nop 0
	v_cndmask_b32_e32 v3, v3, v6, vcc
	v_cndmask_b32_e32 v1, v1, v4, vcc
	v_add_u32_e32 v4, 1, v3
	v_cmp_ge_u32_e32 vcc, v1, v2
	s_nop 1
	v_cndmask_b32_e32 v1, v3, v4, vcc
	v_mul_lo_u32 v3, v2, v1
	v_add_u32_e32 v2, v3, v2
	v_cmp_ne_u32_e32 vcc, v5, v2
	v_mov_b32_e32 v6, v2
	v_mov_b64_e32 v[2:3], s[4:5]
	s_and_saveexec_b64 s[2:3], vcc
	s_cbranch_execz .LBB0_363
	v_mov_b32_e32 v2, 0
	global_load_dword v3, v2, s[4:5] sc1
	s_mov_b64 s[10:11], 0
	s_waitcnt vmcnt(0)
	v_cmp_lt_u32_e32 vcc, v3, v6
	s_and_saveexec_b64 s[8:9], vcc
	s_cbranch_execz .LBB0_362
	s_add_u32 s6, s70, 0x880200
	s_addc_u32 s7, s71, 0
	s_mov_b32 s20, 1
	s_branch .LBB0_355

.LBB0_357:
	global_load_dword v3, v2, s[4:5] sc1
	s_add_i32 s20, s20, 1
	s_mov_b64 s[14:15], -1
	s_waitcnt vmcnt(0)
	v_cmp_ge_u32_e32 vcc, v3, v6
	s_orn2_b64 s[18:19], vcc, exec
	s_branch .LBB0_354

.LBB0_1349:
	s_or_b64 exec, exec, s[6:7]
	s_waitcnt lgkmcnt(0)
	v_cvt_f32_u32_e32 v3, v0
	s_waitcnt vmcnt(0)
	v_readfirstlane_b32 s4, v2
	s_mov_b64 s[6:7], 0
	v_rcp_iflag_f32_e32 v3, v3
	v_add_u32_e32 v1, s4, v1
	v_add_u32_e32 v4, 1, v1
	s_add_u32 s4, s2, 0x3600
	v_mul_f32_e32 v2, 0x4f7ffffe, v3
	v_cvt_u32_f32_e32 v2, v2
	v_sub_u32_e32 v3, 0, v0
	s_addc_u32 s5, s3, 0
	v_mul_lo_u32 v3, v3, v2
	v_mul_hi_u32 v3, v2, v3
	v_add_u32_e32 v2, v2, v3
	v_mul_hi_u32 v2, v1, v2
	v_mul_lo_u32 v3, v2, v0
	v_sub_u32_e32 v1, v1, v3
	v_add_u32_e32 v5, 1, v2
	v_cmp_ge_u32_e32 vcc, v1, v0
	v_sub_u32_e32 v3, v1, v0
	s_nop 0
	v_cndmask_b32_e32 v2, v2, v5, vcc
	v_cndmask_b32_e32 v1, v1, v3, vcc
	v_add_u32_e32 v3, 1, v2
	v_cmp_ge_u32_e32 vcc, v1, v0
	s_nop 1
	v_cndmask_b32_e32 v2, v2, v3, vcc
	v_mul_lo_u32 v1, v0, v2
	v_add_u32_e32 v0, v1, v0
	v_cmp_ne_u32_e32 vcc, v4, v0
	v_mov_b32_e32 v3, v0
	v_mov_b64_e32 v[0:1], s[4:5]
	s_and_saveexec_b64 s[2:3], vcc
	s_cbranch_execz .LBB0_1361
	v_mov_b32_e32 v0, 0
	global_load_dword v1, v0, s[4:5] sc1
	s_mov_b64 s[10:11], 0
	s_waitcnt vmcnt(0)
	v_cmp_lt_u32_e32 vcc, v1, v3
	s_and_saveexec_b64 s[8:9], vcc
	s_cbranch_execz .LBB0_1360
	s_add_u32 s6, s70, 0x880200
	s_addc_u32 s7, s71, 0
	s_mov_b32 s20, 1
	s_branch .LBB0_1353

.LBB0_1355:
	global_load_dword v1, v0, s[4:5] sc1
	s_add_i32 s20, s20, 1
	s_mov_b64 s[14:15], -1
	s_waitcnt vmcnt(0)
	v_cmp_ge_u32_e32 vcc, v1, v3
	s_orn2_b64 s[18:19], vcc, exec
	s_branch .LBB0_1352
